# LN-epilogue acquire invalidate dropped (slots are sc1 both sides); barrier poll without s_sleep
# speedup vs baseline: 1.0039x; 1.0039x over previous
.Lxb1_spin:
	global_load_dword v6, v2, s[42:43] sc1
	s_waitcnt vmcnt(0)
	v_readfirstlane_b32 s51, v6
	s_nop 3
	s_sub_u32 s51, s51, s49
	s_cmp_ge_i32 s51, 0
	s_cbranch_scc1 .Lxb1_done
	s_nop 0
	s_add_u32 s45, s45, 1
	s_cmp_lt_u32 s45, 0x40000
	s_cbranch_scc1 .Lxb1_spin

.LBB0_468:
	s_nop 0
